# s14 + attention odd-tile QK segment: K fragments via v[242:249] so finishSM's late exps/adds/cvt/permlanes are spread over MFMA gaps 5..16 instead of trailing the last MFMA
# speedup vs baseline: 1.0164x; 1.0109x over previous
; __device__ __forceinline__ void finishSM(f32x16& p0, f32x16& p1, float alpha, float& l_reg, bf16x8& pa0, bf16x8& pa1, bf16x8& pa2, bf16x8& pa3) {
;   for (int r = 0; r < 16; ++r) p1[r] = __builtin_amdgcn_exp2f(p1[r]);
;   float ps = 0; for (int r = 0; r < 16; ++r) ps += p0[r]; for (int r = 0; r < 16; ++r) ps += p1[r];
;   { auto rr = __builtin_amdgcn_permlane32_swap(__float_as_uint(ps), __float_as_uint(ps), false, false);
;     ps = __uint_as_float(rr[0]) + __uint_as_float(rr[1]); }
;   l_reg = l_reg * alpha + ps;
;     ...
;   PK4(p0, 0, pa0); PK4(p0, 8, pa1); PK4(p1, 0, pa2); PK4(p1, 8, pa3);
;     ...
; }
; __device__ __forceinline__ void qkt(f32x16& p0, f32x16& p1, const bf16* Ks, const bf16x8* qr, int r32, int hi) {
;   p0 = f32x16{}; p1 = f32x16{};
;   for (int d0 = 0; d0 < 8; ++d0) { int cb = (d0 * 16 + hi * 8) * 2;
;     bf16x8 b0 = *reinterpret_cast<const bf16x8*>((const char*)Ks + KSWZ(r32, cb));
;     bf16x8 b1 = *reinterpret_cast<const bf16x8*>((const char*)Ks + KSWZ(32 + r32, cb));
;     p0 = __builtin_amdgcn_mfma_f32_32x32x16_bf16(b0, qr[d0], p0, 0, 0, 0);
;     p1 = __builtin_amdgcn_mfma_f32_32x32x16_bf16(b1, qr[d0], p1, 0, 0, 0); }
.LBB0_602:
	ds_read_b128 v[64:67], v192 offset:49152
	ds_read_b128 v[68:71], v192 offset:57344
	ds_read_b128 v[242:245], v201 offset:49152
	ds_read_b128 v[246:249], v201 offset:57344
	v_exp_f32_e32 v160, v162
	v_add_f32_e32 v162, 0, v223
	s_waitcnt lgkmcnt(3)
	v_mfma_f32_32x32x16_bf16 v[80:95], v[64:67], v[126:129], 0
	v_add_f32_e32 v162, v224, v162
	v_add_f32_e32 v162, v225, v162
	v_add_f32_e32 v162, v227, v162
	v_add_f32_e32 v162, v229, v162
	v_add_f32_e32 v162, v230, v162
	v_add_f32_e32 v162, v226, v162
	v_add_f32_e32 v162, v228, v162
	s_waitcnt lgkmcnt(2)
	v_mfma_f32_32x32x16_bf16 v[64:79], v[68:71], v[126:129], 0
	v_add_f32_e32 v162, v215, v162
	v_add_f32_e32 v162, v217, v162
	v_add_f32_e32 v162, v219, v162
	v_add_f32_e32 v162, v221, v162
	v_add_f32_e32 v162, v216, v162
	v_add_f32_e32 v162, v218, v162
	v_add_f32_e32 v162, v220, v162
	s_waitcnt lgkmcnt(1)
	v_mfma_f32_32x32x16_bf16 v[80:95], v[242:245], v[122:125], v[80:95]
	v_add_f32_e32 v162, v222, v162
	v_exp_f32_e32 v154, v164
	v_exp_f32_e32 v155, v165
	v_exp_f32_e32 v156, v172
	v_exp_f32_e32 v157, v173
	v_exp_f32_e32 v158, v168
	v_exp_f32_e32 v159, v169
	s_waitcnt lgkmcnt(0)
	v_mfma_f32_32x32x16_bf16 v[64:79], v[246:249], v[122:125], v[64:79]
	ds_read_b128 v[242:245], v200 offset:49152
	ds_read_b128 v[246:249], v200 offset:57344
	v_exp_f32_e32 v161, v163
	v_cvt_pk_bf16_f32 v164, v229, v230
	v_cvt_pk_bf16_f32 v163, v225, v227
	v_cvt_pk_bf16_f32 v165, v226, v228
	v_cvt_pk_bf16_f32 v168, v216, v218
	v_cvt_pk_bf16_f32 v169, v220, v222
	s_waitcnt lgkmcnt(1)
	v_mfma_f32_32x32x16_bf16 v[80:95], v[242:245], v[134:137], v[80:95]
	v_exp_f32_e32 v146, v176
	v_exp_f32_e32 v147, v177
	v_exp_f32_e32 v148, v174
	v_exp_f32_e32 v149, v175
	v_permlane32_swap_b32_e32 v163, v165
	s_waitcnt lgkmcnt(0)
	v_mfma_f32_32x32x16_bf16 v[64:79], v[246:249], v[134:137], v[64:79]
	ds_read_b128 v[242:245], v195 offset:49152
	ds_read_b128 v[246:249], v195 offset:57344
	v_add_f32_e32 v162, v146, v162
	v_add_f32_e32 v162, v147, v162
	v_add_f32_e32 v162, v148, v162
	v_exp_f32_e32 v150, v170
	s_waitcnt lgkmcnt(1)
	v_mfma_f32_32x32x16_bf16 v[80:95], v[242:245], v[130:133], v[80:95]
	v_exp_f32_e32 v151, v171
	v_exp_f32_e32 v152, v166
	v_exp_f32_e32 v153, v167
	v_add_f32_e32 v162, v149, v162
	s_waitcnt lgkmcnt(0)
	v_mfma_f32_32x32x16_bf16 v[64:79], v[246:249], v[130:133], v[64:79]
	ds_read_b128 v[242:245], v194 offset:49152
	ds_read_b128 v[246:249], v194 offset:57344
	v_add_f32_e32 v162, v150, v162
	v_add_f32_e32 v162, v151, v162
	v_add_f32_e32 v162, v152, v162
	v_add_f32_e32 v162, v153, v162
	s_waitcnt lgkmcnt(1)
	v_mfma_f32_32x32x16_bf16 v[80:95], v[242:245], v[118:121], v[80:95]
	v_add_f32_e32 v162, v154, v162
	v_add_f32_e32 v162, v155, v162
	v_add_f32_e32 v162, v156, v162
	v_add_f32_e32 v162, v157, v162
	s_waitcnt lgkmcnt(0)
	v_mfma_f32_32x32x16_bf16 v[64:79], v[246:249], v[118:121], v[64:79]
	ds_read_b128 v[242:245], v193 offset:49152
	ds_read_b128 v[246:249], v193 offset:57344
	v_add_f32_e32 v162, v158, v162
	v_add_f32_e32 v162, v159, v162
	v_add_f32_e32 v162, v160, v162
	v_add_f32_e32 v211, v161, v162
	s_waitcnt lgkmcnt(1)
	v_mfma_f32_32x32x16_bf16 v[80:95], v[242:245], v[114:117], v[80:95]
	v_mov_b32_e32 v212, v211
	v_cvt_pk_bf16_f32 v162, v223, v224
	s_nop 0
	v_permlane32_swap_b32_e32 v211, v212
	s_waitcnt lgkmcnt(0)
	v_mfma_f32_32x32x16_bf16 v[64:79], v[246:249], v[114:117], v[64:79]
	ds_read_b128 v[242:245], v207 offset:49152
	ds_read_b128 v[246:249], v207 offset:57344
	v_permlane32_swap_b32_e32 v162, v164
	v_cvt_pk_bf16_f32 v166, v215, v217
	v_cvt_pk_bf16_f32 v167, v219, v221
	v_cvt_pk_bf16_f32 v170, v146, v147
	s_waitcnt lgkmcnt(1)
	v_mfma_f32_32x32x16_bf16 v[80:95], v[242:245], v[110:113], v[80:95]
	v_cvt_pk_bf16_f32 v171, v148, v149
	v_cvt_pk_bf16_f32 v172, v150, v151
	v_cvt_pk_bf16_f32 v173, v152, v153
	v_cvt_pk_bf16_f32 v174, v154, v155
	s_waitcnt lgkmcnt(0)
	v_mfma_f32_32x32x16_bf16 v[64:79], v[246:249], v[110:113], v[64:79]
	ds_read_b128 v[242:245], v206 offset:49152
	ds_read_b128 v[246:249], v206 offset:57344
	v_cvt_pk_bf16_f32 v175, v156, v157
	v_cvt_pk_bf16_f32 v176, v158, v159
	v_cvt_pk_bf16_f32 v177, v160, v161
	s_waitcnt lgkmcnt(1)
	v_mfma_f32_32x32x16_bf16 v[80:95], v[242:245], v[106:109], v[80:95]
	v_permlane32_swap_b32_e32 v166, v168
	v_permlane32_swap_b32_e32 v167, v169
	v_permlane32_swap_b32_e32 v170, v172
	s_waitcnt lgkmcnt(0)
	v_mfma_f32_32x32x16_bf16 v[64:79], v[246:249], v[106:109], v[64:79]
	v_permlane32_swap_b32_e32 v171, v173
	v_permlane32_swap_b32_e32 v174, v176
	v_permlane32_swap_b32_e32 v175, v177
	v_add_co_u32_e32 v146, vcc, s69, v182
	s_mov_b32 s8, 0xffff0000
	s_nop 0
	v_addc_co_u32_e32 v147, vcc, -1, v183, vcc
	v_add_co_u32_e32 v150, vcc, s8, v182
	s_mov_b32 s8, 0xff6e8000
	s_nop 0
	v_addc_co_u32_e32 v151, vcc, -1, v183, vcc
	v_add_co_u32_e32 v154, vcc, s8, v182
	s_mov_b32 s8, 0xff6f0000
	s_nop 0
	v_addc_co_u32_e32 v155, vcc, -1, v183, vcc
	v_add_co_u32_e32 v158, vcc, s8, v182
	global_load_dwordx4 v[146:149], v[146:147], off
	s_nop 0
	global_load_dwordx4 v[150:153], v[150:151], off
	v_addc_co_u32_e32 v159, vcc, -1, v183, vcc
	global_load_dwordx4 v[154:157], v[154:155], off
	s_nop 0
	global_load_dwordx4 v[158:161], v[158:159], off
	ds_read_b64_tr_b16 v[214:215], v179 offset:0
	ds_read_b64_tr_b16 v[216:217], v179 offset:0x800
	ds_read_b64_tr_b16 v[218:219], v179 offset:0x1000
	ds_read_b64_tr_b16 v[220:221], v179 offset:0x1800
	ds_read_b64_tr_b16 v[222:223], v179 offset:0x2000
	ds_read_b64_tr_b16 v[224:225], v179 offset:0x2800
	ds_read_b64_tr_b16 v[226:227], v179 offset:0x3000
	ds_read_b64_tr_b16 v[228:229], v179 offset:0x3800
	s_waitcnt vmcnt(4)
; #define SBAR() __builtin_amdgcn_sched_barrier(0)
; __device__ __forceinline__ void partialSM(f32x16& p0, f32x16& p1, float& m_reg, float& mn, float& alpha) {
;   constexpr float C = SCALE * 1.4426950408889634f;
;   float pmax = p0[0]; for (int r = 1; r < 16; ++r) pmax = fmaxf(pmax, p0[r]); for (int r = 0; r < 16; ++r) pmax = fmaxf(pmax, p1[r]);
;   { auto rr = __builtin_amdgcn_permlane32_swap(__float_as_uint(pmax), __float_as_uint(pmax), false, false);
;     pmax = fmaxf(__uint_as_float(rr[0]), __uint_as_float(rr[1])); }
;   if (__builtin_expect(__all(pmax - m_reg <= THR / SCALE), 1)) { mn = m_reg; alpha = 1.f; }
;   else { mn = fmaxf(m_reg, pmax); alpha = __builtin_amdgcn_exp2f((m_reg - mn) * C); m_reg = mn; }
;   float mnC = -mn * C;
;   for (int r = 0; r < 16; ++r) p0[r] = fmaf(p0[r], C, mnC); for (int r = 0; r < 16; ++r) p1[r] = fmaf(p1[r], C, mnC);
;   for (int r = 0; r < 16; ++r) p0[r] = __builtin_amdgcn_exp2f(p0[r]);
; template <int D0> __device__ __forceinline__ void pv_one(f32x16& od, int vb, bf16x8 pa0, bf16x8 pa1, bf16x8 pa2, bf16x8 pa3) {
;   const s16x4 l0 = tr_read<v_rd_off(D0, 0, 0)>(vb), h0 = tr_read<v_rd_off(D0, 0, 1)>(vb), l1 = tr_read<v_rd_off(D0, 1, 0)>(vb), h1 = tr_read<v_rd_off(D0, 1, 1)>(vb);
;   const s16x4 l2 = tr_read<v_rd_off(D0, 2, 0)>(vb), h2 = tr_read<v_rd_off(D0, 2, 1)>(vb), l3 = tr_read<v_rd_off(D0, 3, 0)>(vb), h3 = tr_read<v_rd_off(D0, 3, 1)>(vb);
;   asm volatile("s_waitcnt lgkmcnt(0)" ::: "memory"); SBAR();
;     ...
;   od = __builtin_amdgcn_mfma_f32_32x32x16_bf16(pa0, PK(l0, h0), od, 0, 0, 0);
;   od = __builtin_amdgcn_mfma_f32_32x32x16_bf16(pa1, PK(l1, h1), od, 0, 0, 0);
;   od = __builtin_amdgcn_mfma_f32_32x32x16_bf16(pa2, PK(l2, h2), od, 0, 0, 0);
;   od = __builtin_amdgcn_mfma_f32_32x32x16_bf16(pa3, PK(l3, h3), od, 0, 0, 0);
;     ...
; }
; __device__ __forceinline__ void pv_d0(f32x16* o, int vb, bf16x8 pa0, bf16x8 pa1, bf16x8 pa2, bf16x8 pa3) {
;   pv_one<0>(o[0], vb, pa0, pa1, pa2, pa3); pv_one<1>(o[1], vb, pa0, pa1, pa2, pa3); pv_one<2>(o[2], vb, pa0, pa1, pa2, pa3); pv_one<3>(o[3], vb, pa0, pa1, pa2, pa3);
	ds_write_b128 v202, v[102:105] offset:32768
	ds_write_b128 v203, v[142:145] offset:32768
	s_waitcnt lgkmcnt(2)
	s_nop 0
	v_mfma_f32_32x32x16_bf16 v[0:15], v[162:165], v[214:217], v[0:15]
	ds_read_b64_tr_b16 v[214:215], v179 offset:0x200
	ds_read_b64_tr_b16 v[216:217], v179 offset:0xa00
	v_max_f32_e32 v232, v81, v81
	v_max_f32_e32 v233, v80, v80
	v_max_f32_e32 v232, v233, v232
	v_max3_f32 v232, v232, v82, v83
	v_max3_f32 v232, v232, v84, v85
	v_max3_f32 v232, v232, v86, v87
	v_mfma_f32_32x32x16_bf16 v[0:15], v[166:169], v[218:221], v[0:15]
	ds_read_b64_tr_b16 v[218:219], v179 offset:0x1200
	ds_read_b64_tr_b16 v[220:221], v179 offset:0x1a00
	v_max3_f32 v232, v232, v88, v89
	v_max3_f32 v232, v232, v90, v91
	v_max3_f32 v232, v232, v92, v93
	v_max3_f32 v232, v232, v94, v95
	v_max3_f32 v232, v232, v64, v65
	v_max3_f32 v232, v232, v66, v67
	v_mfma_f32_32x32x16_bf16 v[0:15], v[170:173], v[222:225], v[0:15]
	ds_read_b64_tr_b16 v[222:223], v179 offset:0x2200
	ds_read_b64_tr_b16 v[224:225], v179 offset:0x2a00
	v_max3_f32 v232, v232, v68, v69
	v_max3_f32 v232, v232, v70, v71
	v_max3_f32 v232, v232, v72, v73
	v_max3_f32 v232, v232, v74, v75
	v_max3_f32 v232, v232, v76, v77
	v_max3_f32 v232, v232, v78, v79
	v_mfma_f32_32x32x16_bf16 v[0:15], v[174:177], v[226:229], v[0:15]
	ds_read_b64_tr_b16 v[226:227], v179 offset:0x3200
	ds_read_b64_tr_b16 v[228:229], v179 offset:0x3a00
	v_mov_b32_e32 v233, v232
	s_nop 1
	v_permlane32_swap_b32_e32 v232, v233
	v_max_f32_e32 v233, v233, v233
	v_max_f32_e32 v232, v232, v232
	v_max_f32_e32 v232, v232, v233
	s_waitcnt lgkmcnt(0)
	v_mfma_f32_32x32x16_bf16 v[48:63], v[162:165], v[214:217], v[48:63]
	ds_read_b64_tr_b16 v[214:215], v179 offset:0x400
	ds_read_b64_tr_b16 v[216:217], v179 offset:0xc00
	v_sub_f32_e32 v233, v232, v210
	v_cmp_ge_f32_e32 vcc, s68, v233
	v_max_f32_e32 v233, v210, v210
	v_max_f32_e32 v232, v233, v232
	v_sub_f32_e32 v233, v210, v232
	v_mul_f32_e32 v233, 0x3e0293ee, v233
	v_mfma_f32_32x32x16_bf16 v[48:63], v[166:169], v[218:221], v[48:63]
	ds_read_b64_tr_b16 v[218:219], v179 offset:0x1400
	ds_read_b64_tr_b16 v[220:221], v179 offset:0x1c00
	s_cmp_eq_u64 vcc, exec
	s_cselect_b64 s[8:9], -1, 0
	v_exp_f32_e32 v233, v233
	v_mfma_f32_32x32x16_bf16 v[48:63], v[170:173], v[222:225], v[48:63]
	ds_read_b64_tr_b16 v[222:223], v179 offset:0x2400
	ds_read_b64_tr_b16 v[224:225], v179 offset:0x2c00
	v_cndmask_b32_e64 v210, v232, v210, s[8:9]
	v_mul_f32_e32 v213, 0xbe0293ee, v210
	v_fmamk_f32 v80, v80, 0x3e0293ee, v213
	v_fmamk_f32 v81, v81, 0x3e0293ee, v213
	v_fmamk_f32 v82, v82, 0x3e0293ee, v213
	v_fmamk_f32 v83, v83, 0x3e0293ee, v213
	v_mfma_f32_32x32x16_bf16 v[48:63], v[174:177], v[226:229], v[48:63]
	ds_read_b64_tr_b16 v[226:227], v179 offset:0x3400
	ds_read_b64_tr_b16 v[228:229], v179 offset:0x3c00
	v_fmamk_f32 v84, v84, 0x3e0293ee, v213
	v_fmamk_f32 v85, v85, 0x3e0293ee, v213
	v_fmamk_f32 v86, v86, 0x3e0293ee, v213
	v_fmamk_f32 v87, v87, 0x3e0293ee, v213
	v_fmamk_f32 v88, v88, 0x3e0293ee, v213
	v_fmamk_f32 v89, v89, 0x3e0293ee, v213
	s_waitcnt lgkmcnt(0)
	v_mfma_f32_32x32x16_bf16 v[32:47], v[162:165], v[214:217], v[32:47]
	ds_read_b64_tr_b16 v[214:215], v179 offset:0x600
	ds_read_b64_tr_b16 v[216:217], v179 offset:0xe00
	v_fmamk_f32 v90, v90, 0x3e0293ee, v213
	v_fmamk_f32 v91, v91, 0x3e0293ee, v213
	v_fmamk_f32 v92, v92, 0x3e0293ee, v213
	v_fmamk_f32 v93, v93, 0x3e0293ee, v213
	v_fmamk_f32 v94, v94, 0x3e0293ee, v213
	v_fmamk_f32 v95, v95, 0x3e0293ee, v213
	v_mfma_f32_32x32x16_bf16 v[32:47], v[166:169], v[218:221], v[32:47]
	ds_read_b64_tr_b16 v[218:219], v179 offset:0x1600
	ds_read_b64_tr_b16 v[220:221], v179 offset:0x1e00
	v_exp_f32_e32 v80, v80
	v_exp_f32_e32 v81, v81
	v_exp_f32_e32 v82, v82
	v_mfma_f32_32x32x16_bf16 v[32:47], v[170:173], v[222:225], v[32:47]
	ds_read_b64_tr_b16 v[222:223], v179 offset:0x2600
	ds_read_b64_tr_b16 v[224:225], v179 offset:0x2e00
	v_exp_f32_e32 v83, v83
	v_exp_f32_e32 v84, v84
	v_exp_f32_e32 v85, v85
	v_mfma_f32_32x32x16_bf16 v[32:47], v[174:177], v[226:229], v[32:47]
	ds_read_b64_tr_b16 v[226:227], v179 offset:0x3600
	ds_read_b64_tr_b16 v[228:229], v179 offset:0x3e00
	v_exp_f32_e32 v86, v86
	v_exp_f32_e32 v87, v87
	v_exp_f32_e32 v88, v88
	s_waitcnt lgkmcnt(0)
	v_mfma_f32_32x32x16_bf16 v[16:31], v[162:165], v[214:217], v[16:31]
	v_exp_f32_e32 v89, v89
	v_exp_f32_e32 v90, v90
	v_exp_f32_e32 v91, v91
	v_mfma_f32_32x32x16_bf16 v[16:31], v[166:169], v[218:221], v[16:31]
	v_exp_f32_e32 v92, v92
	v_exp_f32_e32 v93, v93
	v_mfma_f32_32x32x16_bf16 v[16:31], v[170:173], v[222:225], v[16:31]
	v_exp_f32_e32 v94, v94
	v_exp_f32_e32 v95, v95
	v_mfma_f32_32x32x16_bf16 v[16:31], v[174:177], v[226:229], v[16:31]
	s_barrier
	s_waitcnt vmcnt(4)
	v_cndmask_b32_e64 v214, v233, 1.0, s[8:9]
	v_cmp_gt_f32_e32 vcc, 1.0, v214
	s_waitcnt vmcnt(7)
	ds_write_b128 v204, v[98:101]
	s_waitcnt vmcnt(6)
	ds_write_b128 v205, v[138:141]
	s_cbranch_vccz .LBB0_606
	s_and_saveexec_b64 s[12:13], s[6:7]
	ds_write_b32 v189, v214 offset:128
	s_or_b64 exec, exec, s[12:13]
	s_waitcnt lgkmcnt(0)
	v_add_u32_e32 v163, v181, v180
	ds_read_b128 v[164:167], v163 offset:224
	ds_read_b128 v[168:171], v163 offset:192
	ds_read_b128 v[172:175], v163 offset:160
	ds_read_b128 v[216:219], v163 offset:128
	s_waitcnt lgkmcnt(3)
	v_pk_mul_f32 v[12:13], v[12:13], v[164:165]
	s_waitcnt lgkmcnt(2)
	v_pk_mul_f32 v[8:9], v[8:9], v[168:169]
	s_waitcnt lgkmcnt(1)
	v_pk_mul_f32 v[4:5], v[4:5], v[172:173]
	v_pk_mul_f32 v[14:15], v[14:15], v[166:167]
	v_pk_mul_f32 v[10:11], v[10:11], v[170:171]
	v_pk_mul_f32 v[6:7], v[6:7], v[174:175]
	s_waitcnt lgkmcnt(0)
	v_pk_mul_f32 v[2:3], v[2:3], v[218:219]
	v_pk_mul_f32 v[0:1], v[0:1], v[216:217]
	v_pk_mul_f32 v[60:61], v[60:61], v[164:165]
	v_pk_mul_f32 v[56:57], v[56:57], v[168:169]
	v_pk_mul_f32 v[52:53], v[52:53], v[172:173]
	v_pk_mul_f32 v[62:63], v[62:63], v[166:167]
	v_pk_mul_f32 v[58:59], v[58:59], v[170:171]
	v_pk_mul_f32 v[54:55], v[54:55], v[174:175]
	v_pk_mul_f32 v[50:51], v[50:51], v[218:219]
	v_pk_mul_f32 v[48:49], v[48:49], v[216:217]
	v_pk_mul_f32 v[44:45], v[44:45], v[164:165]
	v_pk_mul_f32 v[40:41], v[40:41], v[168:169]
	v_pk_mul_f32 v[36:37], v[36:37], v[172:173]
	v_pk_mul_f32 v[46:47], v[46:47], v[166:167]
	v_pk_mul_f32 v[42:43], v[42:43], v[170:171]
	v_pk_mul_f32 v[38:39], v[38:39], v[174:175]
	v_pk_mul_f32 v[34:35], v[34:35], v[218:219]
	v_pk_mul_f32 v[32:33], v[32:33], v[216:217]
	v_pk_mul_f32 v[28:29], v[28:29], v[164:165]
	v_pk_mul_f32 v[24:25], v[24:25], v[168:169]
	v_pk_mul_f32 v[20:21], v[20:21], v[172:173]
	v_pk_mul_f32 v[30:31], v[30:31], v[166:167]
	v_pk_mul_f32 v[26:27], v[26:27], v[170:171]
	v_pk_mul_f32 v[22:23], v[22:23], v[174:175]
	v_pk_mul_f32 v[18:19], v[18:19], v[218:219]
	v_pk_mul_f32 v[16:17], v[16:17], v[216:217]
